# speedup vs baseline: 1.0014x; 1.0014x over previous
; #define SBAR() __builtin_amdgcn_sched_barrier(0)
; #define SWAIT() asm volatile("s_waitcnt vmcnt(4)" ::: "memory")
; #define MASK(P0, P1, t) do { if (BANDED) band_mask(P0, P1, rel00 + (t) * KVBLK, mlo, mhi); } while (0)
; template <bool BANDED, bool FIXED> ...
;     ...
;     SBAR(); if (FIXED) qkt_c(pB0, pB1, (bf16*)((char*)K_lds + SHM_K), qr, r32, hi); else qkt(pB0, pB1, (bf16*)((char*)K_lds + SHM_K), qr, r32, hi, 0.f); MASK(pB0, pB1, j);
;     finishSM(pA0, pA1, alA, l_reg, pa0, pa1, pa2, pa3); SBAR();
;     SLOAD(SO, j + 2); SBAR();
;     pv_d0(o, vb0, pa0, pa1, pa2, pa3); partialSM<FIXED, !BANDED>(pB0, pB1, m_reg, mnB, alB);
;     __syncthreads(); SWAIT(); SWRITE(0, SE);
.LBB0_118:
	s_add_i32 s2, s2, 2
	ds_read_b128 v[10:13], v201 offset:49152
	ds_read_b128 v[176:179], v201 offset:57344
	ds_read_b128 v[188:191], v202 offset:49152
	ds_read_b128 v[192:195], v202 offset:57344
	v_add_u32_e32 v254, vcc_lo, v184
	v_add_u32_e32 v255, vcc_lo, v185
	v_exp_f32_e32 v88, v88
	v_exp_f32_e32 v89, v89
	v_exp_f32_e32 v90, v90
	v_exp_f32_e32 v91, v91
	v_exp_f32_e32 v92, v92
	v_exp_f32_e32 v93, v93
	v_exp_f32_e32 v94, v94
	v_exp_f32_e32 v95, v95
	s_waitcnt lgkmcnt(5)
	v_mfma_f32_32x32x16_bf16 v[112:127], v[2:5], v[156:159], 0
	s_waitcnt lgkmcnt(4)
	v_mfma_f32_32x32x16_bf16 v[96:111], v[6:9], v[156:159], 0
	ds_read_b128 v[2:5], v203 offset:49152
	ds_read_b128 v[6:9], v203 offset:57344
	s_waitcnt lgkmcnt(5)
	v_mfma_f32_32x32x16_bf16 v[112:127], v[10:13], v[152:155], v[112:127]
	s_waitcnt lgkmcnt(4)
	v_mfma_f32_32x32x16_bf16 v[96:111], v[176:179], v[152:155], v[96:111]
	ds_read_b128 v[10:13], v206 offset:49152
	ds_read_b128 v[176:179], v206 offset:57344
	s_waitcnt lgkmcnt(5)
	v_mfma_f32_32x32x16_bf16 v[112:127], v[188:191], v[148:151], v[112:127]
	s_waitcnt lgkmcnt(4)
	v_mfma_f32_32x32x16_bf16 v[96:111], v[192:195], v[148:151], v[96:111]
	ds_read_b128 v[188:191], v204 offset:49152
	ds_read_b128 v[192:195], v204 offset:57344
	s_waitcnt lgkmcnt(5)
	v_mfma_f32_32x32x16_bf16 v[112:127], v[2:5], v[144:147], v[112:127]
	s_waitcnt lgkmcnt(4)
	v_mfma_f32_32x32x16_bf16 v[96:111], v[6:9], v[144:147], v[96:111]
	ds_read_b128 v[2:5], v205 offset:49152
	ds_read_b128 v[6:9], v205 offset:57344
	s_waitcnt vmcnt(0)
	ds_write_b128 v254, v[160:163]
	s_waitcnt lgkmcnt(6)
	v_mfma_f32_32x32x16_bf16 v[112:127], v[10:13], v[140:143], v[112:127]
	s_waitcnt lgkmcnt(5)
	v_mfma_f32_32x32x16_bf16 v[96:111], v[176:179], v[140:143], v[96:111]
	ds_read_b128 v[10:13], v207 offset:49152
	ds_read_b128 v[176:179], v207 offset:57344
	ds_write_b128 v255, v[164:167]
	s_waitcnt lgkmcnt(7)
	v_mfma_f32_32x32x16_bf16 v[112:127], v[188:191], v[136:139], v[112:127]
	s_waitcnt lgkmcnt(6)
	v_mfma_f32_32x32x16_bf16 v[96:111], v[192:195], v[136:139], v[96:111]
	ds_write_b128 v198, v[168:171] offset:32768
	s_waitcnt lgkmcnt(6)
	v_mfma_f32_32x32x16_bf16 v[112:127], v[2:5], v[132:135], v[112:127]
	s_waitcnt lgkmcnt(5)
	v_mfma_f32_32x32x16_bf16 v[96:111], v[6:9], v[132:135], v[96:111]
	ds_write_b128 v199, v[172:175] offset:32768
	s_waitcnt lgkmcnt(4)
	v_mfma_f32_32x32x16_bf16 v[112:127], v[10:13], v[128:131], v[112:127]
	s_waitcnt lgkmcnt(3)
	v_mfma_f32_32x32x16_bf16 v[96:111], v[176:179], v[128:131], v[96:111]
	s_add_i32 s100, s2, 2
	s_mul_i32 s100, s100, 0x60000
	v_add_u32_e32 v254, s100, v14
	v_add_u32_e32 v255, s100, v15
	global_load_dwordx4 v[2:5], v254, s[58:59]
	global_load_dwordx4 v[6:9], v255, s[58:59]
	global_load_dwordx4 v[10:13], v254, s[8:9]
	global_load_dwordx4 v[176:179], v255, s[8:9]
	v_exp_f32_e32 v188, v80
	v_add_f32_e32 v80, 0, v223
	v_add_f32_e32 v80, v225, v80
	v_add_f32_e32 v80, v221, v80
	v_add_f32_e32 v80, v224, v80
	v_add_f32_e32 v80, v220, v80
	v_add_f32_e32 v80, v222, v80
	v_add_f32_e32 v80, v218, v80
	v_add_f32_e32 v80, v219, v80
	v_add_f32_e32 v80, v215, v80
	v_add_f32_e32 v80, v217, v80
	v_add_f32_e32 v80, v214, v80
	v_add_f32_e32 v80, v216, v80
	v_add_f32_e32 v80, v210, v80
	v_exp_f32_e32 v189, v81
	v_add_f32_e32 v80, v213, v80
	v_exp_f32_e32 v190, v82
	v_add_f32_e32 v80, v211, v80
	v_exp_f32_e32 v191, v83
	v_add_f32_e32 v80, v212, v80
	v_exp_f32_e32 v192, v84
	v_add_f32_e32 v80, v188, v80
	v_exp_f32_e32 v193, v85
	v_add_f32_e32 v80, v189, v80
	v_exp_f32_e32 v194, v86
	v_add_f32_e32 v80, v190, v80
	v_exp_f32_e32 v195, v87
	v_add_f32_e32 v80, v191, v80
	v_add_f32_e32 v80, v192, v80
	v_add_f32_e32 v80, v193, v80
	v_add_f32_e32 v80, v194, v80
	v_add_f32_e32 v80, v195, v80
	v_add_f32_e32 v80, v88, v80
	v_add_f32_e32 v80, v89, v80
	v_add_f32_e32 v80, v90, v80
	v_add_f32_e32 v80, v91, v80
	v_add_f32_e32 v80, v92, v80
	v_add_f32_e32 v80, v93, v80
	v_add_f32_e32 v80, v94, v80
	v_add_f32_e32 v80, v95, v80
	v_mov_b32_e32 v81, v80
	s_nop 1
	v_permlane32_swap_b32_e32 v80, v81
	v_add_f32_e32 v80, v80, v81
	v_add_f32_e32 v226, v183, v80
	v_cvt_pk_bf16_f32 v80, v223, v225
	v_cvt_pk_bf16_f32 v81, v221, v224
	v_cvt_pk_bf16_f32 v82, v220, v222
	v_cvt_pk_bf16_f32 v83, v218, v219
	v_cvt_pk_bf16_f32 v84, v215, v217
	v_cvt_pk_bf16_f32 v85, v214, v216
	v_cvt_pk_bf16_f32 v86, v210, v213
	v_cvt_pk_bf16_f32 v87, v211, v212
	v_cvt_pk_bf16_f32 v95, v94, v95
	v_cvt_pk_bf16_f32 v94, v92, v93
	v_cvt_pk_bf16_f32 v93, v90, v91
	v_cvt_pk_bf16_f32 v92, v88, v89
	v_cvt_pk_bf16_f32 v88, v188, v189
	v_cvt_pk_bf16_f32 v89, v190, v191
	v_cvt_pk_bf16_f32 v90, v192, v193
	v_cvt_pk_bf16_f32 v91, v194, v195
	v_permlane32_swap_b32_e32 v80, v82
	v_permlane32_swap_b32_e32 v81, v83
	v_permlane32_swap_b32_e32 v84, v86
	v_permlane32_swap_b32_e32 v85, v87
	v_permlane32_swap_b32_e32 v88, v90
	v_permlane32_swap_b32_e32 v89, v91
	v_permlane32_swap_b32_e32 v93, v95
	v_permlane32_swap_b32_e32 v92, v94
	v_add_u32_e32 v255, vcc_hi, v208
	ds_read_b64_tr_b16 v[210:211], v255 offset:0
	ds_read_b64_tr_b16 v[212:213], v255 offset:0x800
	ds_read_b64_tr_b16 v[214:215], v255 offset:0x1000
	ds_read_b64_tr_b16 v[216:217], v255 offset:0x1800
	ds_read_b64_tr_b16 v[218:219], v255 offset:0x2000
	ds_read_b64_tr_b16 v[220:221], v255 offset:0x2800
	ds_read_b64_tr_b16 v[222:223], v255 offset:0x3000
	ds_read_b64_tr_b16 v[224:225], v255 offset:0x3800
	s_waitcnt lgkmcnt(0)
; #define SBAR() __builtin_amdgcn_sched_barrier(0)
; #define SWAIT() asm volatile("s_waitcnt vmcnt(4)" ::: "memory")
; #define RESC(a) do { if (!FIXED && __any((a) < 1.f)) { if (hi == 0) al_l[r32] = (a); asm volatile("s_waitcnt lgkmcnt(0)" ::: "memory"); \
;     _Pragma("unroll") for (int d = 0; d < 4; ++d) _Pragma("unroll") for (int r = 0; r < 16; ++r) o[d][r] *= al_l[crow(r, hi)]; } } while (0)
; #define MASK(P0, P1, t) do { if (BANDED) band_mask(P0, P1, rel00 + (t) * KVBLK, mlo, mhi); } while (0)
; template <bool BANDED, bool FIXED> ...
;     ...
;     __syncthreads(); SWAIT(); SWRITE(0, SE);
;     RESC(alB); __syncthreads();
;     SBAR(); if (FIXED) qkt_c(pA0, pA1, K_lds, qr, r32, hi); else qkt(pA0, pA1, K_lds, qr, r32, hi, 0.f); MASK(pA0, pA1, j + 1);
;     finishSM(pB0, pB1, alB, l_reg, pa0, pa1, pa2, pa3); SBAR();
;     SLOAD(SE, min(j + 3, NT - 1)); SBAR();
;     pv_d0(o, vb0 + (int)SHM_V, pa0, pa1, pa2, pa3); partialSM<FIXED, !BANDED>(pA0, pA1, m_reg, mnA, alA);
	s_nop 0
	v_mfma_f32_32x32x16_bf16 v[16:31], v[80:83], v[210:213], v[16:31]
	ds_read_b64_tr_b16 v[210:211], v255 offset:0x200
	ds_read_b64_tr_b16 v[212:213], v255 offset:0xa00
	v_mfma_f32_32x32x16_bf16 v[16:31], v[84:87], v[214:217], v[16:31]
	ds_read_b64_tr_b16 v[214:215], v255 offset:0x1200
	ds_read_b64_tr_b16 v[216:217], v255 offset:0x1a00
	v_mfma_f32_32x32x16_bf16 v[16:31], v[88:91], v[218:221], v[16:31]
	ds_read_b64_tr_b16 v[218:219], v255 offset:0x2200
	ds_read_b64_tr_b16 v[220:221], v255 offset:0x2a00
	v_mfma_f32_32x32x16_bf16 v[16:31], v[92:95], v[222:225], v[16:31]
	ds_read_b64_tr_b16 v[222:223], v255 offset:0x3200
	ds_read_b64_tr_b16 v[224:225], v255 offset:0x3a00
	s_waitcnt lgkmcnt(0)
	v_mfma_f32_32x32x16_bf16 v[32:47], v[80:83], v[210:213], v[32:47]
	ds_read_b64_tr_b16 v[210:211], v255 offset:0x400
	ds_read_b64_tr_b16 v[212:213], v255 offset:0xc00
	v_mfma_f32_32x32x16_bf16 v[32:47], v[84:87], v[214:217], v[32:47]
	ds_read_b64_tr_b16 v[214:215], v255 offset:0x1400
	ds_read_b64_tr_b16 v[216:217], v255 offset:0x1c00
	v_mfma_f32_32x32x16_bf16 v[32:47], v[88:91], v[218:221], v[32:47]
	ds_read_b64_tr_b16 v[218:219], v255 offset:0x2400
	ds_read_b64_tr_b16 v[220:221], v255 offset:0x2c00
	v_mfma_f32_32x32x16_bf16 v[32:47], v[92:95], v[222:225], v[32:47]
	ds_read_b64_tr_b16 v[222:223], v255 offset:0x3400
	ds_read_b64_tr_b16 v[224:225], v255 offset:0x3c00
	s_waitcnt lgkmcnt(0)
	v_mfma_f32_32x32x16_bf16 v[48:63], v[80:83], v[210:213], v[48:63]
	ds_read_b64_tr_b16 v[210:211], v255 offset:0x600
	ds_read_b64_tr_b16 v[212:213], v255 offset:0xe00
	v_mfma_f32_32x32x16_bf16 v[48:63], v[84:87], v[214:217], v[48:63]
	ds_read_b64_tr_b16 v[214:215], v255 offset:0x1600
	ds_read_b64_tr_b16 v[216:217], v255 offset:0x1e00
	v_mfma_f32_32x32x16_bf16 v[48:63], v[88:91], v[218:221], v[48:63]
	ds_read_b64_tr_b16 v[218:219], v255 offset:0x2600
	ds_read_b64_tr_b16 v[220:221], v255 offset:0x2e00
	v_mfma_f32_32x32x16_bf16 v[48:63], v[92:95], v[222:225], v[48:63]
	ds_read_b64_tr_b16 v[222:223], v255 offset:0x3600
	ds_read_b64_tr_b16 v[224:225], v255 offset:0x3e00
	s_waitcnt lgkmcnt(0)
	v_mfma_f32_32x32x16_bf16 v[64:79], v[80:83], v[210:213], v[64:79]
	v_exp_f32_e32 v210, v112
	v_exp_f32_e32 v211, v113
	v_exp_f32_e32 v212, v114
	v_exp_f32_e32 v213, v115
	v_mfma_f32_32x32x16_bf16 v[64:79], v[84:87], v[214:217], v[64:79]
	v_exp_f32_e32 v214, v116
	v_exp_f32_e32 v215, v117
	v_exp_f32_e32 v216, v118
	v_exp_f32_e32 v217, v119
	v_mfma_f32_32x32x16_bf16 v[64:79], v[88:91], v[218:221], v[64:79]
	v_exp_f32_e32 v218, v120
	v_exp_f32_e32 v219, v121
	v_exp_f32_e32 v220, v122
	v_exp_f32_e32 v221, v123
	s_mov_b32 s100, vcc_lo
	s_mov_b32 vcc_lo, vcc_hi
	s_mov_b32 vcc_hi, s101
	s_mov_b32 s101, s100
	s_waitcnt lgkmcnt(0)
	s_barrier
	ds_read_b128 v[80:83], v200 offset:32768
	ds_read_b128 v[84:87], v200 offset:40960
	v_mfma_f32_32x32x16_bf16 v[64:79], v[92:95], v[222:225], v[64:79]
	ds_read_b128 v[160:163], v201 offset:32768
	ds_read_b128 v[164:167], v201 offset:40960
	ds_read_b128 v[168:171], v202 offset:32768
	ds_read_b128 v[172:175], v202 offset:40960
	ds_read_b128 v[188:191], v203 offset:32768
	ds_read_b128 v[192:195], v203 offset:40960
	v_exp_f32_e32 v222, v124
	v_exp_f32_e32 v223, v125
	v_exp_f32_e32 v224, v126
	v_exp_f32_e32 v225, v127
	v_add_u32_e32 v254, vcc_lo, v184
	v_add_u32_e32 v255, vcc_lo, v185
	v_exp_f32_e32 v104, v104
	v_exp_f32_e32 v105, v105
	v_exp_f32_e32 v106, v106
	v_exp_f32_e32 v107, v107
	v_exp_f32_e32 v108, v108
	v_exp_f32_e32 v109, v109
	v_exp_f32_e32 v110, v110
	v_exp_f32_e32 v111, v111
	s_waitcnt lgkmcnt(7)
	v_mfma_f32_32x32x16_bf16 v[112:127], v[80:83], v[156:159], 0
	s_waitcnt lgkmcnt(6)
	v_mfma_f32_32x32x16_bf16 v[80:95], v[84:87], v[156:159], 0
	s_waitcnt lgkmcnt(5)
	v_mfma_f32_32x32x16_bf16 v[112:127], v[160:163], v[152:155], v[112:127]
	s_waitcnt lgkmcnt(4)
	v_mfma_f32_32x32x16_bf16 v[80:95], v[164:167], v[152:155], v[80:95]
	ds_read_b128 v[160:163], v206 offset:32768
	ds_read_b128 v[164:167], v206 offset:40960
	s_waitcnt lgkmcnt(5)
	v_mfma_f32_32x32x16_bf16 v[112:127], v[168:171], v[148:151], v[112:127]
	s_waitcnt lgkmcnt(4)
	v_mfma_f32_32x32x16_bf16 v[80:95], v[172:175], v[148:151], v[80:95]
	ds_read_b128 v[168:171], v204 offset:32768
	ds_read_b128 v[172:175], v204 offset:40960
	s_waitcnt lgkmcnt(5)
	v_mfma_f32_32x32x16_bf16 v[112:127], v[188:191], v[144:147], v[112:127]
	s_waitcnt lgkmcnt(4)
	v_mfma_f32_32x32x16_bf16 v[80:95], v[192:195], v[144:147], v[80:95]
	ds_read_b128 v[188:191], v205 offset:32768
	ds_read_b128 v[192:195], v205 offset:40960
	s_waitcnt vmcnt(0)
	ds_write_b128 v254, v[2:5]
	s_waitcnt lgkmcnt(6)
	v_mfma_f32_32x32x16_bf16 v[112:127], v[160:163], v[140:143], v[112:127]
	s_waitcnt lgkmcnt(5)
	v_mfma_f32_32x32x16_bf16 v[80:95], v[164:167], v[140:143], v[80:95]
	ds_read_b128 v[160:163], v207 offset:32768
	ds_read_b128 v[164:167], v207 offset:40960
	ds_write_b128 v255, v[6:9]
	s_waitcnt lgkmcnt(7)
	v_mfma_f32_32x32x16_bf16 v[112:127], v[168:171], v[136:139], v[112:127]
	s_waitcnt lgkmcnt(6)
	v_mfma_f32_32x32x16_bf16 v[80:95], v[172:175], v[136:139], v[80:95]
	ds_write_b128 v198, v[10:13] offset:49152
	s_waitcnt lgkmcnt(6)
	v_mfma_f32_32x32x16_bf16 v[112:127], v[188:191], v[132:135], v[112:127]
	s_waitcnt lgkmcnt(5)
	v_mfma_f32_32x32x16_bf16 v[80:95], v[192:195], v[132:135], v[80:95]
	ds_write_b128 v199, v[176:179] offset:49152
	s_waitcnt lgkmcnt(4)
	v_mfma_f32_32x32x16_bf16 v[112:127], v[160:163], v[128:131], v[112:127]
	s_waitcnt lgkmcnt(3)
; #define SBAR() __builtin_amdgcn_sched_barrier(0)
; #define SWAIT() asm volatile("s_waitcnt vmcnt(4)" ::: "memory")
; #define RESC(a) do { if (!FIXED && __any((a) < 1.f)) { if (hi == 0) al_l[r32] = (a); asm volatile("s_waitcnt lgkmcnt(0)" ::: "memory"); \
;     _Pragma("unroll") for (int d = 0; d < 4; ++d) _Pragma("unroll") for (int r = 0; r < 16; ++r) o[d][r] *= al_l[crow(r, hi)]; } } while (0)
; #define MASK(P0, P1, t) do { if (BANDED) band_mask(P0, P1, rel00 + (t) * KVBLK, mlo, mhi); } while (0)
; __device__ __forceinline__ void finishSM(f32x16& p0, f32x16& p1, float alpha, float& l_reg, bf16x8& pa0, bf16x8& pa1, bf16x8& pa2, bf16x8& pa3) {
; #pragma unroll
;   for (int r = 0; r < 16; ++r) p1[r] = __builtin_amdgcn_exp2f(p1[r]);
;   float ps = 0;
; #pragma unroll
;   for (int r = 0; r < 16; ++r) ps += p0[r];
; #pragma unroll
;   for (int r = 0; r < 16; ++r) ps += p1[r];
;   { auto rr = __builtin_amdgcn_permlane32_swap(__float_as_uint(ps), __float_as_uint(ps), false, false);
;     ps = __uint_as_float(rr[0]) + __uint_as_float(rr[1]); }
;   l_reg = l_reg * alpha + ps;
;     ...
;   PK4(p0, 0, pa0); PK4(p0, 8, pa1); PK4(p1, 0, pa2); PK4(p1, 8, pa3);
;     ...
; }
; template <bool BANDED, bool FIXED> ...
;     ...
;     SBAR(); if (FIXED) qkt_c(pA0, pA1, K_lds, qr, r32, hi); else qkt(pA0, pA1, K_lds, qr, r32, hi, 0.f); MASK(pA0, pA1, j + 1);
;     finishSM(pB0, pB1, alB, l_reg, pa0, pa1, pa2, pa3); SBAR();
;     SLOAD(SE, min(j + 3, NT - 1)); SBAR();
;     pv_d0(o, vb0 + (int)SHM_V, pa0, pa1, pa2, pa3); partialSM<FIXED, !BANDED>(pA0, pA1, m_reg, mnA, alA);
;     __syncthreads(); SWAIT(); SWRITE(1, SO);
;     RESC(alA); __syncthreads();
	v_mfma_f32_32x32x16_bf16 v[80:95], v[164:167], v[128:131], v[80:95]
	s_min_u32 s40, s2, 0xfc
	s_add_i32 s100, s40, 3
	s_mul_i32 s100, s100, 0x60000
	v_add_u32_e32 v254, s100, v14
	v_add_u32_e32 v255, s100, v15
	global_load_dwordx4 v[160:163], v254, s[58:59]
	global_load_dwordx4 v[164:167], v255, s[58:59]
	global_load_dwordx4 v[168:171], v254, s[8:9]
	global_load_dwordx4 v[172:175], v255, s[8:9]
	v_exp_f32_e32 v188, v96
	v_add_f32_e32 v96, 0, v210
	v_add_f32_e32 v96, v211, v96
	v_add_f32_e32 v96, v212, v96
	v_add_f32_e32 v96, v213, v96
	v_add_f32_e32 v96, v214, v96
	v_add_f32_e32 v96, v215, v96
	v_add_f32_e32 v96, v216, v96
	v_add_f32_e32 v96, v217, v96
	v_add_f32_e32 v96, v218, v96
	v_add_f32_e32 v96, v219, v96
	v_add_f32_e32 v96, v220, v96
	v_add_f32_e32 v96, v221, v96
	v_add_f32_e32 v96, v222, v96
	v_exp_f32_e32 v189, v97
	v_add_f32_e32 v96, v223, v96
	v_exp_f32_e32 v190, v98
	v_add_f32_e32 v96, v224, v96
	v_exp_f32_e32 v191, v99
	v_add_f32_e32 v96, v225, v96
	v_exp_f32_e32 v192, v100
	v_add_f32_e32 v96, v188, v96
	v_exp_f32_e32 v193, v101
	v_add_f32_e32 v96, v189, v96
	v_exp_f32_e32 v194, v102
	v_add_f32_e32 v96, v190, v96
	v_exp_f32_e32 v195, v103
	v_add_f32_e32 v96, v191, v96
	v_add_f32_e32 v96, v192, v96
	v_add_f32_e32 v96, v193, v96
	v_add_f32_e32 v96, v194, v96
	v_add_f32_e32 v96, v195, v96
	v_add_f32_e32 v96, v104, v96
	v_add_f32_e32 v96, v105, v96
	v_add_f32_e32 v96, v106, v96
	v_add_f32_e32 v96, v107, v96
	v_add_f32_e32 v96, v108, v96
	v_add_f32_e32 v96, v109, v96
	v_add_f32_e32 v96, v110, v96
	v_add_f32_e32 v96, v111, v96
	v_mov_b32_e32 v97, v96
	s_nop 1
	v_permlane32_swap_b32_e32 v96, v97
	v_add_f32_e32 v96, v96, v97
	v_add_f32_e32 v183, v226, v96
	v_cvt_pk_bf16_f32 v96, v210, v211
	v_cvt_pk_bf16_f32 v97, v212, v213
	v_cvt_pk_bf16_f32 v98, v214, v215
	v_cvt_pk_bf16_f32 v99, v216, v217
	v_cvt_pk_bf16_f32 v100, v218, v219
	v_cvt_pk_bf16_f32 v101, v220, v221
	v_cvt_pk_bf16_f32 v102, v222, v223
	v_cvt_pk_bf16_f32 v103, v224, v225
	v_cvt_pk_bf16_f32 v111, v110, v111
	v_cvt_pk_bf16_f32 v110, v108, v109
	v_cvt_pk_bf16_f32 v109, v106, v107
	v_cvt_pk_bf16_f32 v108, v104, v105
	v_cvt_pk_bf16_f32 v104, v188, v189
	v_cvt_pk_bf16_f32 v105, v190, v191
	v_cvt_pk_bf16_f32 v106, v192, v193
	v_cvt_pk_bf16_f32 v107, v194, v195
	v_permlane32_swap_b32_e32 v96, v98
	v_permlane32_swap_b32_e32 v97, v99
	v_permlane32_swap_b32_e32 v100, v102
	v_permlane32_swap_b32_e32 v101, v103
	v_permlane32_swap_b32_e32 v104, v106
	v_permlane32_swap_b32_e32 v105, v107
	v_permlane32_swap_b32_e32 v109, v111
	v_permlane32_swap_b32_e32 v108, v110
	v_add_u32_e32 v255, vcc_hi, v208
	ds_read_b64_tr_b16 v[210:211], v255 offset:0
	ds_read_b64_tr_b16 v[212:213], v255 offset:0x800
	ds_read_b64_tr_b16 v[214:215], v255 offset:0x1000
	ds_read_b64_tr_b16 v[216:217], v255 offset:0x1800
	ds_read_b64_tr_b16 v[218:219], v255 offset:0x2000
	ds_read_b64_tr_b16 v[220:221], v255 offset:0x2800
	ds_read_b64_tr_b16 v[222:223], v255 offset:0x3000
	ds_read_b64_tr_b16 v[224:225], v255 offset:0x3800
	s_waitcnt lgkmcnt(0)
	s_nop 0
	v_mfma_f32_32x32x16_bf16 v[16:31], v[96:99], v[210:213], v[16:31]
	ds_read_b64_tr_b16 v[210:211], v255 offset:0x200
	ds_read_b64_tr_b16 v[212:213], v255 offset:0xa00
	v_mfma_f32_32x32x16_bf16 v[16:31], v[100:103], v[214:217], v[16:31]
	ds_read_b64_tr_b16 v[214:215], v255 offset:0x1200
	ds_read_b64_tr_b16 v[216:217], v255 offset:0x1a00
	v_mfma_f32_32x32x16_bf16 v[16:31], v[104:107], v[218:221], v[16:31]
	ds_read_b64_tr_b16 v[218:219], v255 offset:0x2200
	ds_read_b64_tr_b16 v[220:221], v255 offset:0x2a00
	v_mfma_f32_32x32x16_bf16 v[16:31], v[108:111], v[222:225], v[16:31]
	ds_read_b64_tr_b16 v[222:223], v255 offset:0x3200
	ds_read_b64_tr_b16 v[224:225], v255 offset:0x3a00
	s_waitcnt lgkmcnt(0)
	v_mfma_f32_32x32x16_bf16 v[32:47], v[96:99], v[210:213], v[32:47]
	ds_read_b64_tr_b16 v[210:211], v255 offset:0x400
	ds_read_b64_tr_b16 v[212:213], v255 offset:0xc00
	v_mfma_f32_32x32x16_bf16 v[32:47], v[100:103], v[214:217], v[32:47]
	ds_read_b64_tr_b16 v[214:215], v255 offset:0x1400
	ds_read_b64_tr_b16 v[216:217], v255 offset:0x1c00
	v_mfma_f32_32x32x16_bf16 v[32:47], v[104:107], v[218:221], v[32:47]
	ds_read_b64_tr_b16 v[218:219], v255 offset:0x2400
	ds_read_b64_tr_b16 v[220:221], v255 offset:0x2c00
	v_mfma_f32_32x32x16_bf16 v[32:47], v[108:111], v[222:225], v[32:47]
	ds_read_b64_tr_b16 v[222:223], v255 offset:0x3400
	ds_read_b64_tr_b16 v[224:225], v255 offset:0x3c00
	s_waitcnt lgkmcnt(0)
	v_mfma_f32_32x32x16_bf16 v[48:63], v[96:99], v[210:213], v[48:63]
	ds_read_b64_tr_b16 v[210:211], v255 offset:0x600
	ds_read_b64_tr_b16 v[212:213], v255 offset:0xe00
	v_mfma_f32_32x32x16_bf16 v[48:63], v[100:103], v[214:217], v[48:63]
	ds_read_b64_tr_b16 v[214:215], v255 offset:0x1600
	ds_read_b64_tr_b16 v[216:217], v255 offset:0x1e00
	v_mfma_f32_32x32x16_bf16 v[48:63], v[104:107], v[218:221], v[48:63]
	ds_read_b64_tr_b16 v[218:219], v255 offset:0x2600
	ds_read_b64_tr_b16 v[220:221], v255 offset:0x2e00
	v_mfma_f32_32x32x16_bf16 v[48:63], v[108:111], v[222:225], v[48:63]
	ds_read_b64_tr_b16 v[222:223], v255 offset:0x3600
	ds_read_b64_tr_b16 v[224:225], v255 offset:0x3e00
	s_waitcnt lgkmcnt(0)
	v_mfma_f32_32x32x16_bf16 v[64:79], v[96:99], v[210:213], v[64:79]
	v_exp_f32_e32 v210, v124
	v_exp_f32_e32 v213, v125
	v_exp_f32_e32 v211, v126
	v_exp_f32_e32 v212, v127
	v_mfma_f32_32x32x16_bf16 v[64:79], v[100:103], v[214:217], v[64:79]
	v_exp_f32_e32 v215, v120
	v_exp_f32_e32 v217, v121
	v_exp_f32_e32 v214, v122
	v_exp_f32_e32 v216, v123
	s_cmpk_gt_u32 s2, 0xfc
	v_mfma_f32_32x32x16_bf16 v[64:79], v[104:107], v[218:221], v[64:79]
	v_exp_f32_e32 v221, v114
	v_exp_f32_e32 v220, v116
	v_exp_f32_e32 v218, v118
	v_exp_f32_e32 v219, v119
	s_mov_b32 s100, vcc_lo
	s_mov_b32 vcc_lo, vcc_hi
	s_mov_b32 vcc_hi, s101
	s_mov_b32 s101, s100
	s_waitcnt lgkmcnt(0)
	s_barrier
; #define SBAR() __builtin_amdgcn_sched_barrier(0)
; #define RESC(a) do { if (!FIXED && __any((a) < 1.f)) { if (hi == 0) al_l[r32] = (a); asm volatile("s_waitcnt lgkmcnt(0)" ::: "memory"); \
;     _Pragma("unroll") for (int d = 0; d < 4; ++d) _Pragma("unroll") for (int r = 0; r < 16; ++r) o[d][r] *= al_l[crow(r, hi)]; } } while (0)
; #define MASK(P0, P1, t) do { if (BANDED) band_mask(P0, P1, rel00 + (t) * KVBLK, mlo, mhi); } while (0)
; __device__ __forceinline__ void finishSM(f32x16& p0, f32x16& p1, float alpha, float& l_reg, bf16x8& pa0, bf16x8& pa1, bf16x8& pa2, bf16x8& pa3) {
; #pragma unroll
;   for (int r = 0; r < 16; ++r) p1[r] = __builtin_amdgcn_exp2f(p1[r]);
;   float ps = 0;
; #pragma unroll
;   for (int r = 0; r < 16; ++r) ps += p0[r];
; #pragma unroll
;   for (int r = 0; r < 16; ++r) ps += p1[r];
;   { auto rr = __builtin_amdgcn_permlane32_swap(__float_as_uint(ps), __float_as_uint(ps), false, false);
;     ps = __uint_as_float(rr[0]) + __uint_as_float(rr[1]); }
;   l_reg = l_reg * alpha + ps;
;     ...
;   PK4(p0, 0, pa0); PK4(p0, 8, pa1); PK4(p1, 0, pa2); PK4(p1, 8, pa3);
;     ...
; }
; template <bool BANDED, bool FIXED> ...
;     ...
;   SBAR(); if (FIXED) qkt_c(pB0, pB1, (bf16*)((char*)K_lds + SHM_K), qr, r32, hi); else qkt(pB0, pB1, (bf16*)((char*)K_lds + SHM_K), qr, r32, hi, 0.f); MASK(pB0, pB1, NT - 1);
;   finishSM(pA0, pA1, alA, l_reg, pa0, pa1, pa2, pa3); SBAR();
;   pv_d0(o, vb0, pa0, pa1, pa2, pa3); partialSM<FIXED, !BANDED>(pB0, pB1, m_reg, mnB, alB);
;   __syncthreads(); RESC(alB);
;   finishSM(pB0, pB1, alB, l_reg, pa0, pa1, pa2, pa3); SBAR();
;   pv_d0(o, vb0 + (int)SHM_V, pa0, pa1, pa2, pa3);
	ds_read_b128 v[2:5], v200 offset:49152
	ds_read_b128 v[6:9], v200 offset:57344
	v_mfma_f32_32x32x16_bf16 v[64:79], v[108:111], v[222:225], v[64:79]
	v_exp_f32_e32 v223, v112
	v_exp_f32_e32 v225, v113
	v_exp_f32_e32 v224, v115
	v_exp_f32_e32 v222, v117
	s_cbranch_scc0 .LBB0_118
	v_mov_b32_e32 v188, 0x3c0881c4
	v_mov_b32_e32 v189, 0xbab64f3b
	v_mov_b32_e32 v190, 1
	v_bfrev_b32_e32 v191, 0.5
	v_mov_b32_e32 v192, 0xf149f2ca
	v_mov_b32_e32 v193, 0xff800000
	v_mov_b32_e32 v194, 0x41b17218
	v_not_b32_e32 v195, 63
	v_add_u32_e32 v255, vcc_hi, v208
	v_add_u32_e32 v254, s101, v208
	v_exp_f32_e32 v12, v80
	v_exp_f32_e32 v13, v81
	v_exp_f32_e32 v14, v82
	s_waitcnt lgkmcnt(1)
	v_mfma_f32_32x32x16_bf16 v[112:127], v[2:5], v[156:159], 0
	v_exp_f32_e32 v15, v83
	v_exp_f32_e32 v80, v84
	v_exp_f32_e32 v81, v85
	v_exp_f32_e32 v82, v86
	v_exp_f32_e32 v83, v87
	v_exp_f32_e32 v84, v88
	v_exp_f32_e32 v85, v89
	s_waitcnt lgkmcnt(0)
	v_mfma_f32_32x32x16_bf16 v[96:111], v[6:9], v[156:159], 0
	ds_read_b128 v[2:5], v201 offset:49152
	ds_read_b128 v[6:9], v201 offset:57344
	v_exp_f32_e32 v86, v90
	v_exp_f32_e32 v87, v91
	v_exp_f32_e32 v88, v92
	v_exp_f32_e32 v89, v93
	v_exp_f32_e32 v90, v94
	v_exp_f32_e32 v91, v95
	s_waitcnt lgkmcnt(1)
	v_mfma_f32_32x32x16_bf16 v[112:127], v[2:5], v[152:155], v[112:127]
	v_cvt_pk_bf16_f32 v10, v210, v213
	v_cvt_pk_bf16_f32 v11, v211, v212
	s_waitcnt lgkmcnt(0)
	v_mfma_f32_32x32x16_bf16 v[96:111], v[6:9], v[152:155], v[96:111]
	ds_read_b128 v[2:5], v202 offset:49152
	ds_read_b128 v[6:9], v202 offset:57344
	s_waitcnt lgkmcnt(1)
	v_mfma_f32_32x32x16_bf16 v[112:127], v[2:5], v[148:151], v[112:127]
	s_waitcnt lgkmcnt(0)
	v_mfma_f32_32x32x16_bf16 v[96:111], v[6:9], v[148:151], v[96:111]
	ds_read_b128 v[2:5], v203 offset:49152
	ds_read_b128 v[6:9], v203 offset:57344
	s_waitcnt lgkmcnt(1)
	v_mfma_f32_32x32x16_bf16 v[112:127], v[2:5], v[144:147], v[112:127]
	s_waitcnt lgkmcnt(0)
	v_mfma_f32_32x32x16_bf16 v[96:111], v[6:9], v[144:147], v[96:111]
	ds_read_b128 v[2:5], v206 offset:49152
	ds_read_b128 v[6:9], v206 offset:57344
	s_waitcnt lgkmcnt(1)
	v_mfma_f32_32x32x16_bf16 v[112:127], v[2:5], v[140:143], v[112:127]
	s_waitcnt lgkmcnt(0)
	v_mfma_f32_32x32x16_bf16 v[96:111], v[6:9], v[140:143], v[96:111]
	ds_read_b128 v[2:5], v204 offset:49152
	ds_read_b128 v[6:9], v204 offset:57344
	s_waitcnt lgkmcnt(1)
	v_mfma_f32_32x32x16_bf16 v[112:127], v[2:5], v[136:139], v[112:127]
	s_waitcnt lgkmcnt(0)
	v_mfma_f32_32x32x16_bf16 v[96:111], v[6:9], v[136:139], v[96:111]
	ds_read_b128 v[2:5], v205 offset:49152
	ds_read_b128 v[6:9], v205 offset:57344
	s_waitcnt lgkmcnt(1)
	v_mfma_f32_32x32x16_bf16 v[112:127], v[2:5], v[132:135], v[112:127]
	s_waitcnt lgkmcnt(0)
	v_mfma_f32_32x32x16_bf16 v[96:111], v[6:9], v[132:135], v[96:111]
	ds_read_b128 v[2:5], v207 offset:49152
	ds_read_b128 v[6:9], v207 offset:57344
	s_waitcnt lgkmcnt(1)
	v_mfma_f32_32x32x16_bf16 v[112:127], v[2:5], v[128:131], v[112:127]
	v_add_f32_e32 v2, 0, v223
	v_add_f32_e32 v2, v225, v2
	v_add_f32_e32 v2, v221, v2
	v_add_f32_e32 v2, v224, v2
	v_add_f32_e32 v2, v220, v2
	v_add_f32_e32 v2, v222, v2
	v_add_f32_e32 v2, v218, v2
	v_add_f32_e32 v2, v219, v2
	v_add_f32_e32 v2, v215, v2
	v_add_f32_e32 v2, v217, v2
	v_add_f32_e32 v2, v214, v2
	v_add_f32_e32 v2, v216, v2
	v_add_f32_e32 v2, v210, v2
	v_add_f32_e32 v2, v213, v2
	v_add_f32_e32 v2, v211, v2
	v_add_f32_e32 v2, v212, v2
	v_add_f32_e32 v2, v12, v2
	v_add_f32_e32 v2, v13, v2
	v_add_f32_e32 v2, v14, v2
	v_add_f32_e32 v2, v15, v2
	v_add_f32_e32 v2, v80, v2
	v_add_f32_e32 v2, v81, v2
	v_add_f32_e32 v2, v82, v2
	v_add_f32_e32 v2, v83, v2
	v_add_f32_e32 v2, v84, v2
	v_add_f32_e32 v2, v85, v2
	v_add_f32_e32 v2, v86, v2
	v_add_f32_e32 v2, v87, v2
	v_add_f32_e32 v2, v88, v2
	v_add_f32_e32 v2, v89, v2
	v_add_f32_e32 v2, v90, v2
	v_add_f32_e32 v2, v91, v2
	s_waitcnt lgkmcnt(0)
	v_mfma_f32_32x32x16_bf16 v[96:111], v[6:9], v[128:131], v[96:111]
	v_mov_b32_e32 v3, v2
	v_cvt_pk_bf16_f32 v4, v223, v225
	v_cvt_pk_bf16_f32 v5, v221, v224
	v_cvt_pk_bf16_f32 v6, v220, v222
	v_cvt_pk_bf16_f32 v7, v218, v219
	s_nop 1
	v_permlane32_swap_b32_e32 v2, v3
	v_permlane32_swap_b32_e32 v4, v6
	v_permlane32_swap_b32_e32 v5, v7
	v_cvt_pk_bf16_f32 v8, v215, v217
	v_cvt_pk_bf16_f32 v9, v214, v216
	v_cvt_pk_bf16_f32 v12, v12, v13
	v_cvt_pk_bf16_f32 v13, v14, v15
	v_cvt_pk_bf16_f32 v14, v80, v81
	v_cvt_pk_bf16_f32 v15, v82, v83
	v_cvt_pk_bf16_f32 v80, v84, v85
	v_cvt_pk_bf16_f32 v81, v86, v87
	v_cvt_pk_bf16_f32 v82, v88, v89
	v_cvt_pk_bf16_f32 v83, v90, v91
	s_nop 0
	v_permlane32_swap_b32_e32 v8, v10
	v_permlane32_swap_b32_e32 v9, v11
	v_permlane32_swap_b32_e32 v12, v14
	v_permlane32_swap_b32_e32 v13, v15
	v_permlane32_swap_b32_e32 v80, v82
	v_permlane32_swap_b32_e32 v81, v83
	ds_read_b64_tr_b16 v[84:85], v255 offset:0
	ds_read_b64_tr_b16 v[86:87], v255 offset:0x800
	ds_read_b64_tr_b16 v[88:89], v255 offset:0x1000
	ds_read_b64_tr_b16 v[90:91], v255 offset:0x1800
	ds_read_b64_tr_b16 v[92:93], v255 offset:0x2000
	ds_read_b64_tr_b16 v[94:95], v255 offset:0x2800
	ds_read_b64_tr_b16 v[128:129], v255 offset:0x3000
	ds_read_b64_tr_b16 v[130:131], v255 offset:0x3800
	s_waitcnt lgkmcnt(0)
	s_nop 0
	v_mfma_f32_32x32x16_bf16 v[16:31], v[4:7], v[84:87], v[16:31]
	ds_read_b64_tr_b16 v[84:85], v255 offset:0x200
	ds_read_b64_tr_b16 v[86:87], v255 offset:0xa00
	v_mfma_f32_32x32x16_bf16 v[16:31], v[8:11], v[88:91], v[16:31]
	ds_read_b64_tr_b16 v[88:89], v255 offset:0x1200
	ds_read_b64_tr_b16 v[90:91], v255 offset:0x1a00
	v_mfma_f32_32x32x16_bf16 v[16:31], v[12:15], v[92:95], v[16:31]
	ds_read_b64_tr_b16 v[92:93], v255 offset:0x2200
	ds_read_b64_tr_b16 v[94:95], v255 offset:0x2a00
	v_mfma_f32_32x32x16_bf16 v[16:31], v[80:83], v[128:131], v[16:31]
	ds_read_b64_tr_b16 v[128:129], v255 offset:0x3200
	ds_read_b64_tr_b16 v[130:131], v255 offset:0x3a00
	s_waitcnt lgkmcnt(0)
; #define SBAR() __builtin_amdgcn_sched_barrier(0)
; #define RESC(a) do { if (!FIXED && __any((a) < 1.f)) { if (hi == 0) al_l[r32] = (a); asm volatile("s_waitcnt lgkmcnt(0)" ::: "memory"); \
;     _Pragma("unroll") for (int d = 0; d < 4; ++d) _Pragma("unroll") for (int r = 0; r < 16; ++r) o[d][r] *= al_l[crow(r, hi)]; } } while (0)
; #define MASK(P0, P1, t) do { if (BANDED) band_mask(P0, P1, rel00 + (t) * KVBLK, mlo, mhi); } while (0)
; template <bool BANDED, bool FIXED> ...
;     ...
;   SBAR(); if (FIXED) qkt_c(pB0, pB1, (bf16*)((char*)K_lds + SHM_K), qr, r32, hi); else qkt(pB0, pB1, (bf16*)((char*)K_lds + SHM_K), qr, r32, hi, 0.f); MASK(pB0, pB1, NT - 1);
;   finishSM(pA0, pA1, alA, l_reg, pa0, pa1, pa2, pa3); SBAR();
;   pv_d0(o, vb0, pa0, pa1, pa2, pa3); partialSM<FIXED, !BANDED>(pB0, pB1, m_reg, mnB, alB);
;   __syncthreads(); RESC(alB);
;   finishSM(pB0, pB1, alB, l_reg, pa0, pa1, pa2, pa3); SBAR();
;   pv_d0(o, vb0 + (int)SHM_V, pa0, pa1, pa2, pa3);
;   if (!BANDED && wave >= 4) __builtin_amdgcn_s_setprio(0);
	v_mfma_f32_32x32x16_bf16 v[32:47], v[4:7], v[84:87], v[32:47]
	ds_read_b64_tr_b16 v[84:85], v255 offset:0x400
	ds_read_b64_tr_b16 v[86:87], v255 offset:0xc00
	v_mfma_f32_32x32x16_bf16 v[32:47], v[8:11], v[88:91], v[32:47]
	ds_read_b64_tr_b16 v[88:89], v255 offset:0x1400
	ds_read_b64_tr_b16 v[90:91], v255 offset:0x1c00
	v_mfma_f32_32x32x16_bf16 v[32:47], v[12:15], v[92:95], v[32:47]
	ds_read_b64_tr_b16 v[92:93], v255 offset:0x2400
	ds_read_b64_tr_b16 v[94:95], v255 offset:0x2c00
	v_mfma_f32_32x32x16_bf16 v[32:47], v[80:83], v[128:131], v[32:47]
	ds_read_b64_tr_b16 v[128:129], v255 offset:0x3400
	ds_read_b64_tr_b16 v[130:131], v255 offset:0x3c00
	s_waitcnt lgkmcnt(0)
	v_mfma_f32_32x32x16_bf16 v[48:63], v[4:7], v[84:87], v[48:63]
	ds_read_b64_tr_b16 v[84:85], v255 offset:0x600
	ds_read_b64_tr_b16 v[86:87], v255 offset:0xe00
	v_mfma_f32_32x32x16_bf16 v[48:63], v[8:11], v[88:91], v[48:63]
	ds_read_b64_tr_b16 v[88:89], v255 offset:0x1600
	ds_read_b64_tr_b16 v[90:91], v255 offset:0x1e00
	v_mfma_f32_32x32x16_bf16 v[48:63], v[12:15], v[92:95], v[48:63]
	ds_read_b64_tr_b16 v[92:93], v255 offset:0x2600
	ds_read_b64_tr_b16 v[94:95], v255 offset:0x2e00
	v_mfma_f32_32x32x16_bf16 v[48:63], v[80:83], v[128:131], v[48:63]
	ds_read_b64_tr_b16 v[128:129], v255 offset:0x3600
	ds_read_b64_tr_b16 v[130:131], v255 offset:0x3e00
	s_waitcnt lgkmcnt(0)
	v_mfma_f32_32x32x16_bf16 v[64:79], v[4:7], v[84:87], v[64:79]
	v_exp_f32_e32 v6, v112
	v_exp_f32_e32 v7, v113
	v_exp_f32_e32 v84, v126
	v_exp_f32_e32 v85, v127
	v_add_f32_e32 v4, 0, v6
	v_add_f32_e32 v4, v7, v4
	v_exp_f32_e32 v86, v96
	v_mfma_f32_32x32x16_bf16 v[64:79], v[8:11], v[88:91], v[64:79]
	v_exp_f32_e32 v8, v114
	v_exp_f32_e32 v9, v115
	v_exp_f32_e32 v10, v116
	v_exp_f32_e32 v11, v117
	v_add_f32_e32 v4, v8, v4
	v_add_f32_e32 v4, v9, v4
	v_add_f32_e32 v4, v10, v4
	v_mfma_f32_32x32x16_bf16 v[64:79], v[12:15], v[92:95], v[64:79]
	v_exp_f32_e32 v12, v118
	v_exp_f32_e32 v13, v119
	v_exp_f32_e32 v14, v120
	v_exp_f32_e32 v15, v121
	v_add_f32_e32 v4, v11, v4
	v_add_f32_e32 v4, v12, v4
	v_add_f32_e32 v4, v13, v4
	v_mfma_f32_32x32x16_bf16 v[64:79], v[80:83], v[128:131], v[64:79]
	v_exp_f32_e32 v80, v122
	v_exp_f32_e32 v81, v123
	v_exp_f32_e32 v82, v124
	v_add_f32_e32 v4, v14, v4
	v_exp_f32_e32 v83, v125
	v_add_f32_e32 v4, v15, v4
	v_add_f32_e32 v4, v80, v4
	v_add_f32_e32 v4, v81, v4
	v_add_f32_e32 v4, v82, v4
	v_exp_f32_e32 v87, v97
	v_add_f32_e32 v4, v83, v4
	v_exp_f32_e32 v88, v98
	v_add_f32_e32 v4, v84, v4
	v_exp_f32_e32 v89, v99
	v_add_f32_e32 v4, v85, v4
	v_exp_f32_e32 v90, v100
	v_add_f32_e32 v4, v86, v4
	v_exp_f32_e32 v91, v101
	v_add_f32_e32 v4, v87, v4
	v_exp_f32_e32 v92, v102
	v_add_f32_e32 v4, v88, v4
	v_exp_f32_e32 v93, v103
	v_add_f32_e32 v4, v89, v4
	v_exp_f32_e32 v94, v104
	v_add_f32_e32 v4, v90, v4
	v_exp_f32_e32 v95, v105
	v_add_f32_e32 v4, v91, v4
	v_exp_f32_e32 v96, v106
	v_add_f32_e32 v4, v92, v4
	v_exp_f32_e32 v97, v107
	v_add_f32_e32 v4, v93, v4
	v_exp_f32_e32 v98, v108
	v_add_f32_e32 v4, v94, v4
	v_exp_f32_e32 v99, v109
	v_add_f32_e32 v4, v95, v4
	v_exp_f32_e32 v100, v110
	v_add_f32_e32 v4, v96, v4
	v_exp_f32_e32 v101, v111
	v_add_f32_e32 v4, v97, v4
	v_add_f32_e32 v4, v98, v4
	v_add_f32_e32 v4, v99, v4
	v_add_f32_e32 v4, v100, v4
	v_add_f32_e32 v4, v101, v4
	v_mov_b32_e32 v5, v4
	s_nop 1
	v_permlane32_swap_b32_e32 v4, v5
	v_cvt_pk_bf16_f32 v6, v6, v7
	v_cvt_pk_bf16_f32 v7, v8, v9
	v_cvt_pk_bf16_f32 v8, v10, v11
	v_cvt_pk_bf16_f32 v9, v12, v13
	v_cvt_pk_bf16_f32 v10, v14, v15
	v_cvt_pk_bf16_f32 v11, v80, v81
	v_cvt_pk_bf16_f32 v12, v82, v83
	v_cvt_pk_bf16_f32 v13, v84, v85
	v_cvt_pk_bf16_f32 v80, v86, v87
	v_cvt_pk_bf16_f32 v81, v88, v89
	v_cvt_pk_bf16_f32 v82, v90, v91
	v_cvt_pk_bf16_f32 v83, v92, v93
	v_cvt_pk_bf16_f32 v84, v94, v95
	v_cvt_pk_bf16_f32 v85, v96, v97
	v_cvt_pk_bf16_f32 v86, v98, v99
	v_cvt_pk_bf16_f32 v87, v100, v101
	s_barrier
	v_permlane32_swap_b32_e32 v6, v8
	v_permlane32_swap_b32_e32 v7, v9
	v_permlane32_swap_b32_e32 v10, v12
	v_permlane32_swap_b32_e32 v11, v13
	v_permlane32_swap_b32_e32 v80, v82
	v_permlane32_swap_b32_e32 v81, v83
	v_permlane32_swap_b32_e32 v84, v86
	v_permlane32_swap_b32_e32 v85, v87
	ds_read_b64_tr_b16 v[88:89], v254 offset:0
	ds_read_b64_tr_b16 v[90:91], v254 offset:0x800
	ds_read_b64_tr_b16 v[92:93], v254 offset:0x1000
	ds_read_b64_tr_b16 v[94:95], v254 offset:0x1800
	ds_read_b64_tr_b16 v[96:97], v254 offset:0x2000
	ds_read_b64_tr_b16 v[98:99], v254 offset:0x2800
	ds_read_b64_tr_b16 v[100:101], v254 offset:0x3000
	ds_read_b64_tr_b16 v[102:103], v254 offset:0x3800
	s_waitcnt lgkmcnt(0)
	s_nop 0
	v_mfma_f32_32x32x16_bf16 v[16:31], v[6:9], v[88:91], v[16:31]
	ds_read_b64_tr_b16 v[88:89], v254 offset:0x200
	ds_read_b64_tr_b16 v[90:91], v254 offset:0xa00
	v_mfma_f32_32x32x16_bf16 v[16:31], v[10:13], v[92:95], v[16:31]
	ds_read_b64_tr_b16 v[92:93], v254 offset:0x1200
	ds_read_b64_tr_b16 v[94:95], v254 offset:0x1a00
	v_mfma_f32_32x32x16_bf16 v[16:31], v[80:83], v[96:99], v[16:31]
	ds_read_b64_tr_b16 v[96:97], v254 offset:0x2200
	ds_read_b64_tr_b16 v[98:99], v254 offset:0x2a00
	v_mfma_f32_32x32x16_bf16 v[16:31], v[84:87], v[100:103], v[16:31]
	ds_read_b64_tr_b16 v[100:101], v254 offset:0x3200
	ds_read_b64_tr_b16 v[102:103], v254 offset:0x3a00
	s_waitcnt lgkmcnt(0)
	v_mfma_f32_32x32x16_bf16 v[32:47], v[6:9], v[88:91], v[32:47]
	ds_read_b64_tr_b16 v[88:89], v254 offset:0x400
	ds_read_b64_tr_b16 v[90:91], v254 offset:0xc00
	v_mfma_f32_32x32x16_bf16 v[32:47], v[10:13], v[92:95], v[32:47]
	ds_read_b64_tr_b16 v[92:93], v254 offset:0x1400
	ds_read_b64_tr_b16 v[94:95], v254 offset:0x1c00
	v_mfma_f32_32x32x16_bf16 v[32:47], v[80:83], v[96:99], v[32:47]
	ds_read_b64_tr_b16 v[96:97], v254 offset:0x2400
	ds_read_b64_tr_b16 v[98:99], v254 offset:0x2c00
	v_mfma_f32_32x32x16_bf16 v[32:47], v[84:87], v[100:103], v[32:47]
	ds_read_b64_tr_b16 v[100:101], v254 offset:0x3400
	ds_read_b64_tr_b16 v[102:103], v254 offset:0x3c00
	s_waitcnt lgkmcnt(0)
	v_mfma_f32_32x32x16_bf16 v[48:63], v[6:9], v[88:91], v[48:63]
	ds_read_b64_tr_b16 v[88:89], v254 offset:0x600
	ds_read_b64_tr_b16 v[90:91], v254 offset:0xe00
	v_mfma_f32_32x32x16_bf16 v[48:63], v[10:13], v[92:95], v[48:63]
	ds_read_b64_tr_b16 v[92:93], v254 offset:0x1600
	ds_read_b64_tr_b16 v[94:95], v254 offset:0x1e00
	v_mfma_f32_32x32x16_bf16 v[48:63], v[80:83], v[96:99], v[48:63]
	ds_read_b64_tr_b16 v[96:97], v254 offset:0x2600
	ds_read_b64_tr_b16 v[98:99], v254 offset:0x2e00
	v_mfma_f32_32x32x16_bf16 v[48:63], v[84:87], v[100:103], v[48:63]
	ds_read_b64_tr_b16 v[100:101], v254 offset:0x3600
	ds_read_b64_tr_b16 v[102:103], v254 offset:0x3e00
	s_waitcnt lgkmcnt(0)
	v_mfma_f32_32x32x16_bf16 v[64:79], v[6:9], v[88:91], v[64:79]
	s_and_b64 vcc, exec, s[22:23]
	v_mfma_f32_32x32x16_bf16 v[64:79], v[10:13], v[92:95], v[64:79]
	v_mfma_f32_32x32x16_bf16 v[64:79], v[80:83], v[96:99], v[64:79]
	v_mfma_f32_32x32x16_bf16 v[64:79], v[84:87], v[100:103], v[64:79]
	s_cbranch_vccz .LBB0_121
	s_setprio 0
